# attention item pairing permuted within sequence quarters so every workgroup gets 6-7 extra tiles instead of 1-9
# speedup vs baseline: 1.0017x; 1.0017x over previous
.LBB0_1073:
	v_readlane_b32 s98, v252, 49
	s_mov_b32 s100, 0xb3e26a01
	s_mov_b32 s101, 0x974d5f8c
	s_cmp_eq_u32 s93, 1
	s_cselect_b32 s100, 0xec16fd9, s100
	s_cselect_b32 s101, 0x542b37a8, s101
	s_cmp_eq_u32 s93, 2
	s_cselect_b32 s100, 0x5a47018b, s100
	s_cselect_b32 s101, 0xd9ec23f6, s101
	s_cmp_eq_u32 s93, 3
	s_cselect_b32 s100, 0xd2673104, s100
	s_cselect_b32 s101, 0xfaec59b8, s101
	s_lshr_b32 s98, s98, 1
	s_lshl_b32 s98, s98, 2
	s_lshr_b64 s[100:101], s[100:101], s98
	s_and_b32 s100, s100, 15
	s_sub_i32 s101, 15, s100
	s_lshl_b32 s0, s93, 4
	s_bitcmp0_b32 s93, 0
	v_readlane_b32 s1, v252, 49
	v_readlane_b32 s2, v253, 2
	s_cselect_b32 s100, s100, s101
	s_cselect_b32 s1, s1, s2
	s_add_i32 s0, s0, s100
	v_mov_b32 v37, v178
	s_sub_i32 s68, 63, s0
	v_ashrrev_i32_e32 v225, 6, v37
	v_lshlrev_b32_e32 v207, 3, v225
	v_bfe_u32 v208, v37, 2, 3
	s_lshl_b32 s33, s68, 6
	v_or_b32_e32 v226, v207, v208
	v_add_u32_e32 v184, s33, v226
	v_ashrrev_i32_e32 v185, 31, v184
	s_and_b32 s2, s1, 1
	v_and_b32_e32 v36, 3, v37
	v_lshl_add_u64 v[34:35], v[184:185], 0, s[70:71]
	s_nop 0
	v_lshlrev_b64 v[2:3], 10, v[34:35]
	v_readlane_b32 s18, v252, 5
	v_readlane_b32 s19, v252, 6
	v_lshl_or_b32 v42, s2, 2, v36
	v_bfe_u32 v199, v37, 5, 1
	v_lshl_add_u64 v[2:3], s[18:19], 0, v[2:3]
	v_lshlrev_b32_e32 v0, 7, v42
	v_lshl_add_u64 v[2:3], v[2:3], 0, v[0:1]
	v_lshlrev_b32_e32 v0, 4, v199
	v_lshl_add_u64 v[2:3], v[2:3], 0, v[0:1]
	s_movk_i32 s3, 0x60
	s_mov_b32 s74, s0
	global_load_dwordx4 v[162:165], v[2:3], off
	global_load_dwordx4 v[166:169], v[2:3], off offset:32
	global_load_dwordx4 v[170:173], v[2:3], off offset:64
	global_load_dwordx4 v[174:177], v[2:3], off offset:96
	v_mad_u64_u32 v[2:3], s[0:1], v34, s3, v[180:181]
	s_nop 7
	s_nop 4
	v_mad_i32_i24 v3, v35, s3, v3
	s_lshl_b32 s72, s2, 4
	v_lshl_add_u64 v[2:3], v[2:3], 0, s[72:73]
	v_lshlrev_b32_e32 v0, 2, v36
	s_nop 0
	s_or_b32 s20, s2, s65
	v_lshl_add_u64 v[2:3], v[2:3], 0, v[0:1]
	s_nop 1
	v_readlane_b32 s14, v252, 17
	v_readlane_b32 s15, v252, 18
	global_load_dword v0, v[2:3], off
	global_load_dword v223, v[2:3], off offset:32
	global_load_dword v185, v[2:3], off offset:64
	s_lshl_b32 s2, s20, 15
	s_mov_b64 s[10:11], s[14:15]
	v_lshrrev_b32_e32 v3, 4, v37
	s_nop 1
	v_readlane_b32 s16, v252, 19
	v_readlane_b32 s17, v252, 20
	s_add_u32 s0, s10, s2
	v_lshlrev_b32_e32 v38, 3, v37
	v_xor_b32_e32 v3, v3, v37
	v_readlane_b32 s18, v252, 21
	v_readlane_b32 s19, v252, 22
	s_mov_b64 s[12:13], s[16:17]
	s_addc_u32 s1, s11, 0
	v_and_b32_e32 v2, 0xffffffc0, v38
	v_lshlrev_b32_e32 v3, 3, v3
	s_add_u32 s2, s12, s2
	v_and_or_b32 v186, v3, 56, v2
	v_lshlrev_b32_e32 v224, 4, v37
	s_mov_b32 s4, 0x1ffffffc
	s_addc_u32 s3, s13, 0
	s_ashr_i32 s72, s68, 4
	v_and_b32_e32 v2, 0xfc0, v224
	v_and_or_b32 v3, v225, s4, v36
	v_ashrrev_i32_e32 v187, 31, v186
	v_lshl_add_u32 v188, v3, 3, v2
	v_lshl_add_u64 v[2:3], v[186:187], 1, s[0:1]
	s_min_i32 s0, s72, 0
	v_ashrrev_i32_e32 v189, 31, v188
	s_ashr_i32 s1, s0, 31
	v_add_u32_e32 v200, 0, v224
	s_nop 0
	v_readfirstlane_b32 s99, v200
	v_lshl_add_u64 v[4:5], v[188:189], 1, s[2:3]
	s_lshl_b64 s[0:1], s[0:1], 13
	v_readfirstlane_b32 s2, v200
	v_lshl_add_u64 v[6:7], v[2:3], 0, s[0:1]
	s_mov_b32 m0, s2
	v_add_u32_e32 v213, 0x2000, v200
	global_load_lds_dwordx4 v[6:7], off
	v_lshl_add_u64 v[6:7], v[4:5], 0, s[0:1]
	v_readfirstlane_b32 s0, v213
	s_mov_b32 m0, s0
	s_min_i32 s0, s72, 1
	s_ashr_i32 s1, s0, 31
	v_add_u32_e32 v214, 0x4000, v200
	s_lshl_b64 s[0:1], s[0:1], 13
	v_readfirstlane_b32 s2, v214
	global_load_lds_dwordx4 v[6:7], off
	v_lshl_add_u64 v[6:7], v[2:3], 0, s[0:1]
	s_mov_b32 m0, s2
	v_add_u32_e32 v215, 0x6000, v200
	global_load_lds_dwordx4 v[6:7], off
	v_lshl_add_u64 v[6:7], v[4:5], 0, s[0:1]
	v_readfirstlane_b32 s0, v215
	s_mov_b32 m0, s0
	s_min_i32 s0, s72, 2
	s_ashr_i32 s1, s0, 31
	v_add_u32_e32 v216, 0x8000, v200
	s_lshl_b64 s[0:1], s[0:1], 13
	v_readfirstlane_b32 s2, v216
	global_load_lds_dwordx4 v[6:7], off
	v_lshl_add_u64 v[6:7], v[2:3], 0, s[0:1]
	s_mov_b32 m0, s2
	v_add_u32_e32 v217, 0xa000, v200
	global_load_lds_dwordx4 v[6:7], off
	v_lshl_add_u64 v[6:7], v[4:5], 0, s[0:1]
	v_readfirstlane_b32 s0, v217
	s_mov_b32 m0, s0
	s_min_i32 s0, s72, 3
	s_ashr_i32 s1, s0, 31
	v_add_u32_e32 v218, 0xc000, v200
	s_lshl_b64 s[0:1], s[0:1], 13
	v_readfirstlane_b32 s2, v218
	global_load_lds_dwordx4 v[6:7], off
	v_lshl_add_u64 v[2:3], v[2:3], 0, s[0:1]
	s_mov_b32 m0, s2
	v_add_u32_e32 v221, 0xe000, v200
	global_load_lds_dwordx4 v[2:3], off
	v_lshl_add_u64 v[2:3], v[4:5], 0, s[0:1]
	v_readfirstlane_b32 s0, v221
	s_mov_b32 m0, s0
	s_sub_i32 s0, s33, 31
	global_load_lds_dwordx4 v[2:3], off
	v_subrev_u32_e32 v2, 31, v184
	v_ashrrev_i32_e32 v40, 4, v2
	v_lshrrev_b32_e32 v2, 5, v37
	v_bfe_u32 v3, v37, 1, 3
	v_bitop3_b32 v2, v2, v3, 1 bitop3:0x6c
	v_lshlrev_b32_e32 v201, 4, v2
	v_bitop3_b32 v2, v199, v3, 2 bitop3:0x36
	v_lshlrev_b32_e32 v202, 4, v2
	v_bitop3_b32 v2, v199, v3, 4 bitop3:0x36
	v_lshlrev_b32_e32 v4, 7, v37
	v_lshlrev_b32_e32 v203, 4, v2
	v_bitop3_b32 v2, v199, v3, 6 bitop3:0x36
	s_ashr_i32 s92, s0, 4
	v_lshlrev_b32_e32 v204, 4, v2
	v_and_b32_e32 v2, 0xf80, v4
	s_waitcnt vmcnt(0)
	v_add_u32_e32 v205, 0, v2
	s_cmp_gt_i32 s72, -1
	s_mov_b32 s64, s20
	v_lshlrev_b32_e32 v210, 2, v199
	s_cselect_b64 s[66:67], -1, 0
	s_cmp_lt_i32 s72, 0
	v_add_u32_e32 v222, v205, v201
	v_add_u32_e32 v219, v205, v202
	v_add_u32_e32 v212, v205, v203
	v_add_u32_e32 v211, v205, v204
	s_nop 2
	v_readlane_b32 s8, v252, 11
	v_readlane_b32 s9, v252, 12
	s_mov_b64 s[14:15], s[18:19]
	s_waitcnt vmcnt(0) lgkmcnt(0)
	s_barrier
	s_cbranch_scc1 .LBB0_1077
	ds_read_b128 v[2:5], v222
	ds_read_b128 v[6:9], v222 offset:4096
	ds_read_b128 v[44:47], v219
	ds_read_b128 v[48:51], v219 offset:4096
	s_cmp_gt_i32 s92, 62
	s_waitcnt lgkmcnt(3)
	v_mfma_f32_32x32x16_bf16 v[18:33], v[2:5], v[162:165], 0
	s_waitcnt lgkmcnt(2)
	v_mfma_f32_32x32x16_bf16 v[2:17], v[6:9], v[162:165], 0
	s_waitcnt lgkmcnt(1)
	v_mfma_f32_32x32x16_bf16 v[18:33], v[44:47], v[166:169], v[18:33]
	s_waitcnt lgkmcnt(0)
	v_mfma_f32_32x32x16_bf16 v[2:17], v[48:51], v[166:169], v[2:17]
	ds_read_b128 v[44:47], v212
	ds_read_b128 v[48:51], v212 offset:4096
	s_waitcnt lgkmcnt(1)
	v_mfma_f32_32x32x16_bf16 v[18:33], v[44:47], v[170:173], v[18:33]
	s_waitcnt lgkmcnt(0)
	v_mfma_f32_32x32x16_bf16 v[2:17], v[48:51], v[170:173], v[2:17]
	ds_read_b128 v[44:47], v211
	ds_read_b128 v[48:51], v211 offset:4096
	s_waitcnt lgkmcnt(1)
	v_mfma_f32_32x32x16_bf16 v[18:33], v[44:47], v[174:177], v[18:33]
	s_waitcnt lgkmcnt(0)
	v_mfma_f32_32x32x16_bf16 v[2:17], v[48:51], v[174:177], v[2:17]
	s_cbranch_scc1 .LBB0_1076
	v_sub_u32_e32 v39, v40, v210
	v_cmp_gt_i32_e64 s[58:59], 26, v39
	v_cmp_gt_i32_e64 s[62:63], 27, v39
	v_cmp_gt_i32_e64 s[56:57], 25, v39
	s_and_b64 s[58:59], s[62:63], s[58:59]
	v_cmp_gt_i32_e64 s[54:55], 24, v39
	s_and_b64 s[56:57], s[58:59], s[56:57]
	v_cmp_gt_i32_e64 s[52:53], 19, v39
	s_and_b64 s[54:55], s[56:57], s[54:55]
	v_cmp_gt_i32_e64 s[50:51], 18, v39
	s_and_b64 s[52:53], s[54:55], s[52:53]
	v_cmp_gt_i32_e64 s[48:49], 17, v39
	s_and_b64 s[50:51], s[52:53], s[50:51]
	v_cmp_gt_i32_e64 s[46:47], 16, v39
	s_and_b64 s[48:49], s[50:51], s[48:49]
	v_cmp_gt_i32_e64 s[44:45], 11, v39
	s_and_b64 s[46:47], s[48:49], s[46:47]
	v_cmp_gt_i32_e64 s[42:43], 10, v39
	s_and_b64 s[44:45], s[46:47], s[44:45]
	v_cmp_gt_i32_e64 s[40:41], 9, v39
	s_and_b64 s[42:43], s[44:45], s[42:43]
	v_cmp_gt_i32_e64 s[38:39], 8, v39
	s_and_b64 s[40:41], s[42:43], s[40:41]
	v_cmp_gt_i32_e64 s[36:37], 3, v39
	s_and_b64 s[38:39], s[40:41], s[38:39]
	v_cmp_gt_i32_e64 s[34:35], 2, v39
	s_and_b64 s[36:37], s[38:39], s[36:37]
	v_cmp_gt_i32_e64 s[30:31], 1, v39
	s_and_b64 s[34:35], s[36:37], s[34:35]
	v_cmp_gt_i32_e64 s[28:29], 0, v39
	s_and_b64 s[30:31], s[34:35], s[30:31]
	s_and_b64 s[28:29], s[30:31], s[28:29]
	v_cmp_gt_i32_e64 s[60:61], 58, v39
	v_cndmask_b32_e64 v18, v18, v196, s[28:29]
	v_cmp_gt_i32_e64 s[28:29], 59, v39
	v_cmp_gt_i32_e64 s[26:27], 57, v39
	v_cmp_gt_i32_e64 s[24:25], 56, v39
	v_cndmask_b32_e64 v17, v17, v196, s[28:29]
	s_and_b64 s[28:29], s[28:29], s[60:61]
	s_and_b64 s[26:27], s[28:29], s[26:27]
	v_cmp_gt_i32_e64 s[22:23], 51, v39
	s_and_b64 s[24:25], s[26:27], s[24:25]
	v_cmp_gt_i32_e64 s[20:21], 50, v39
	s_and_b64 s[22:23], s[24:25], s[22:23]
	v_cmp_gt_i32_e64 s[18:19], 49, v39
	s_and_b64 s[20:21], s[22:23], s[20:21]
	v_cmp_gt_i32_e64 s[16:17], 48, v39
	s_and_b64 s[18:19], s[20:21], s[18:19]
	v_cmp_gt_i32_e64 s[14:15], 43, v39
	s_and_b64 s[16:17], s[18:19], s[16:17]
	v_cmp_gt_i32_e64 s[12:13], 42, v39
	s_and_b64 s[14:15], s[16:17], s[14:15]
	v_cmp_gt_i32_e64 s[8:9], 41, v39
	s_and_b64 s[12:13], s[14:15], s[12:13]
	v_cmp_gt_i32_e64 s[6:7], 40, v39
	s_and_b64 s[8:9], s[12:13], s[8:9]
	v_cmp_gt_i32_e64 s[4:5], 35, v39
	s_and_b64 s[6:7], s[8:9], s[6:7]
	v_cmp_gt_i32_e64 s[2:3], 34, v39
	s_and_b64 s[4:5], s[6:7], s[4:5]
	v_cmp_gt_i32_e64 s[0:1], 33, v39
	s_and_b64 s[2:3], s[4:5], s[2:3]
	v_cmp_gt_i32_e32 vcc, 32, v39
	s_and_b64 s[0:1], s[2:3], s[0:1]
	s_and_b64 vcc, s[0:1], vcc
	v_cndmask_b32_e64 v33, v33, v196, s[62:63]
	v_cndmask_b32_e64 v32, v32, v196, s[58:59]
	v_cndmask_b32_e64 v31, v31, v196, s[56:57]
	v_cndmask_b32_e64 v30, v30, v196, s[54:55]
	v_cndmask_b32_e64 v29, v29, v196, s[52:53]
	v_cndmask_b32_e64 v28, v28, v196, s[50:51]
	v_cndmask_b32_e64 v27, v27, v196, s[48:49]
	v_cndmask_b32_e64 v26, v26, v196, s[46:47]
	v_cndmask_b32_e64 v25, v25, v196, s[44:45]
	v_cndmask_b32_e64 v24, v24, v196, s[42:43]
	v_cndmask_b32_e64 v23, v23, v196, s[40:41]
	v_cndmask_b32_e64 v22, v22, v196, s[38:39]
	v_cndmask_b32_e64 v21, v21, v196, s[36:37]
	v_cndmask_b32_e64 v20, v20, v196, s[34:35]
	v_cndmask_b32_e64 v19, v19, v196, s[30:31]
	v_cndmask_b32_e64 v16, v16, v196, s[28:29]
	v_cndmask_b32_e64 v15, v15, v196, s[26:27]
	v_cndmask_b32_e64 v14, v14, v196, s[24:25]
	v_cndmask_b32_e64 v13, v13, v196, s[22:23]
	v_cndmask_b32_e64 v12, v12, v196, s[20:21]
	v_cndmask_b32_e64 v11, v11, v196, s[18:19]
	v_cndmask_b32_e64 v10, v10, v196, s[16:17]
	v_cndmask_b32_e64 v9, v9, v196, s[14:15]
	v_cndmask_b32_e64 v8, v8, v196, s[12:13]
	v_cndmask_b32_e64 v7, v7, v196, s[8:9]
	v_cndmask_b32_e64 v6, v6, v196, s[6:7]
	v_cndmask_b32_e64 v5, v5, v196, s[4:5]
	v_cndmask_b32_e64 v4, v4, v196, s[2:3]
	v_cndmask_b32_e64 v3, v3, v196, s[0:1]
	v_cndmask_b32_e32 v2, v2, v196, vcc
